# out-projection phases: the full vmcnt(0) the compiler placed ahead of every unit's first K iteration is removed (the LDS-DMA prefetch it guarded targets the epilogue area, not the K ring) and units af
# baseline (speedup 1.0000x reference)
.LBB0_594:
	s_ashr_i32 s81, s80, 31
	s_lshl_b64 s[84:85], s[80:81], 20
	s_add_u32 s84, s29, s84
	s_addc_u32 s85, s34, s85
	s_and_b64 s[86:87], s[82:83], exec
	s_cselect_b32 s81, s85, s95
	s_cselect_b32 vcc_lo, s84, s94
	s_ashr_i32 s79, s78, 31
	s_lshl_b64 s[86:87], s[78:79], 20
	s_add_u32 s86, s35, s86
	s_addc_u32 s87, s38, s87
	s_and_b64 s[2:3], s[82:83], exec
	s_cselect_b32 s79, s87, s93
	s_cselect_b32 vcc_hi, s86, s92
	s_lshl_b32 s88, s88, 8
	s_ashr_i32 s89, s88, 31
	s_lshl_b64 s[2:3], s[88:89], 2
	s_add_u32 s2, s90, s2
	s_addc_u32 s3, s91, s3
	s_add_i32 m0, s14, s41
	s_add_u32 s90, s94, 0x80080
	global_load_lds_dwordx4 v239, s[2:3]
	s_addc_u32 s91, s95, 0
	s_add_u32 s89, s92, 0x100
	s_addc_u32 s14, s93, 0
	s_mov_b32 s20, -2
	s_add_u32 s2, s90, 0xfff80080
	s_addc_u32 s3, s91, -1
	s_add_i32 s67, 0, 0x10000
	s_cmp_eq_u32 s20, 28
	s_cselect_b32 s95, s81, s3
	s_cselect_b32 s94, vcc_lo, s2
	s_cselect_b32 s93, s79, s14
	s_cselect_b32 s92, vcc_hi, s89
	s_add_i32 s76, 0, 0x14000
	s_add_i32 m0, s39, 0xc000
	global_load_lds_dwordx4 v230, s[90:91]
	s_add_i32 m0, s39, 0xe000
	s_nop 0
	global_load_lds_dwordx4 v232, s[90:91]
	s_cmp_lg_u32 s54, 1
	s_cbranch_scc1 .Lds2_0
	s_waitcnt vmcnt(8)

.LBB0_964:
	s_ashr_i32 s79, s78, 31
	s_lshl_b64 s[82:83], s[78:79], 20
	s_add_u32 s82, s14, s82
	s_addc_u32 s83, s15, s83
	s_and_b64 s[84:85], s[80:81], exec
	s_cselect_b32 s79, s83, s93
	s_cselect_b32 s96, s82, s92
	s_ashr_i32 s77, s76, 31
	s_lshl_b64 s[84:85], s[76:77], 20
	s_add_u32 s84, s24, s84
	s_addc_u32 s85, s26, s85
	s_and_b64 vcc, s[80:81], exec
	s_cselect_b32 s77, s85, s91
	s_cselect_b32 vcc_lo, s84, s90
	s_lshl_b32 s86, s86, 8
	s_ashr_i32 s87, s86, 31
	s_lshl_b64 s[74:75], s[86:87], 2
	s_add_u32 s74, s88, s74
	s_addc_u32 s75, s89, s75
	s_add_i32 m0, s71, s40
	s_add_u32 s88, s92, 0x80080
	global_load_lds_dwordx4 v239, s[74:75]
	s_addc_u32 s89, s93, 0
	s_add_u32 s87, s90, 0x100
	s_addc_u32 vcc_hi, s91, 0
	s_mov_b32 s71, -2
	s_add_u32 s67, s88, 0xfff80080
	s_addc_u32 s74, s89, -1
	s_add_i32 s75, 0, 0x10000
	s_cmp_eq_u32 s71, 28
	s_cselect_b32 s93, s79, s74
	s_cselect_b32 s92, s96, s67
	s_cselect_b32 s91, s77, vcc_hi
	s_cselect_b32 s90, vcc_lo, s87
	s_add_i32 s67, 0, 0x14000
	s_add_i32 m0, s28, 0xc000
	global_load_lds_dwordx4 v230, s[88:89]
	s_add_i32 m0, s28, 0xe000
	s_nop 0
	global_load_lds_dwordx4 v232, s[88:89]
	s_cmp_lg_u32 s94, 1
	s_cbranch_scc1 .Lds4_0
	s_waitcnt vmcnt(8)

.LBB0_1289:
	s_lshl_b32 s80, s96, 8
	s_ashr_i32 s81, s80, 31
	s_lshl_b64 s[86:87], s[80:81], 2
	s_add_u32 s84, s84, s86
	s_addc_u32 s85, s85, s87
	s_add_i32 m0, s94, s41
	s_add_u32 s81, s82, 0x100
	global_load_lds_dwordx4 v239, s[84:85]
	s_addc_u32 s96, s83, 0
	s_cmp_eq_u32 s54, 5
	s_cselect_b32 vcc_lo, 66, -2
	s_bfe_u32 s86, s1, 0x20003
	s_cmp_eq_u32 s86, 3
	s_cselect_b32 s86, -8, 0
	s_cmp_eq_u32 s54, 5
	s_cselect_b32 s86, s86, 0
	s_add_i32 vcc_lo, vcc_lo, s86
	s_add_u32 s82, s78, 0x100
	s_addc_u32 s83, s79, 0
	s_add_i32 s94, 0, 0x10000
	s_cmpk_eq_i32 vcc_lo, 0x54
	s_cselect_b32 s87, s75, s83
	s_cselect_b32 s86, s74, s82
	s_cselect_b32 s85, s77, s96
	s_cselect_b32 s84, s76, s81
	s_add_i32 vcc_hi, 0, 0x14000
	s_add_i32 m0, s29, 0xc000
	global_load_lds_dwordx4 v230, s[78:79]
	s_add_i32 m0, s29, 0xe000
	s_nop 0
	global_load_lds_dwordx4 v232, s[78:79]
	s_cmp_lg_u32 s54, 1
	s_cbranch_scc1 .Lds6_0
	s_waitcnt vmcnt(8)
